# P5 leftover tiles on 48 idle P6 workgroups; their dependent P6 work split into 16-row tasks over all 512 threads
# speedup vs baseline: 1.0157x; 1.0157x over previous
.LBB0_936:
	s_or_b64 exec, exec, s[4:5]
	s_mov_b32 s97, 0
.Lt5_entry:
	s_cmp_lg_u32 s97, 0
	s_cbranch_scc1 .Lt5_nocp
	s_lshl_b32 s4, s2, 9
	v_add_lshl_u32 v0, s4, v176, 5
	s_add_u32 s4, s30, 0x10a00000
	s_addc_u32 s5, s31, 0
	global_load_dwordx4 v[2:5], v0, s[4:5]
	global_load_dwordx4 v[6:9], v0, s[4:5] offset:16
	s_add_u32 s4, s30, 0xc600000
	s_addc_u32 s5, s31, 0
	s_waitcnt vmcnt(0)
	global_store_dwordx4 v0, v[2:5], s[4:5]
	global_store_dwordx4 v0, v[6:9], s[4:5] offset:16
.Lt5_nocp:
	v_mov_b32_e32 v14, v176
	s_waitcnt lgkmcnt(0)
	s_barrier
	s_cmpk_gt_i32 s2, 0x62f
	s_nop 0
	v_readfirstlane_b32 s24, v14
	s_cbranch_scc1 .LBB0_948
	v_lshlrev_b32_e32 v0, 4, v14
	v_add_u32_e32 v1, 0x2000, v0
	v_ashrrev_i32_e32 v2, 31, v1
	v_lshrrev_b32_e32 v2, 22, v2
	v_add_u32_e32 v2, v1, v2
	v_ashrrev_i32_e32 v8, 10, v2
	v_mul_i32_i24_e32 v2, 0x400, v8
	v_sub_u32_e32 v1, v1, v2
	v_lshrrev_b32_e32 v2, 4, v1
	v_bitop3_b32 v1, v2, v1, 32 bitop3:0x6c
	v_ashrrev_i32_e32 v2, 31, v1
	v_lshrrev_b32_e32 v2, 26, v2
	v_add_u32_e32 v2, v1, v2
	v_lshlrev_b32_e32 v3, 3, v8
	v_ashrrev_i32_e32 v9, 6, v2
	v_and_b32_e32 v3, -16, v3
	v_add_u32_e32 v3, v9, v3
	v_and_b32_e32 v4, 3, v9
	s_mov_b32 s4, 0xfffe0
	v_lshrrev_b32_e32 v5, 2, v3
	v_lshlrev_b32_e32 v6, 1, v3
	v_and_b32_e32 v2, 0xc0, v2
	v_and_or_b32 v4, v3, s4, v4
	v_and_b32_e32 v5, 4, v5
	v_and_b32_e32 v6, 24, v6
	v_sub_u32_e32 v1, v1, v2
	v_mov_b32_e32 v2, 1
	v_or3_b32 v4, v4, v5, v6
	v_lshlrev_b32_e32 v5, 5, v8
	v_ashrrev_i16_sdwa v1, v2, sext(v1) dst_sel:DWORD dst_unused:UNUSED_PAD src0_sel:DWORD src1_sel:BYTE_0
	v_and_b32_e32 v5, 32, v5
	v_bfe_i32 v10, v1, 0, 16
	v_add_lshl_u32 v1, v5, v10, 1
	v_lshl_add_u32 v128, v4, 12, v1
	v_lshl_add_u32 v130, v3, 12, v1
	v_bfe_i32 v1, v14, 27, 1
	v_lshrrev_b32_e32 v1, 22, v1
	v_add_u32_e32 v1, v0, v1
	v_and_b32_e32 v1, 0xfffffc00, v1
	v_sub_u32_e32 v0, v0, v1
	v_lshrrev_b32_e32 v1, 4, v0
	v_bitop3_b32 v1, v1, v0, 32 bitop3:0x6c
	v_ashrrev_i32_e32 v0, 31, v0
	v_lshrrev_b32_e32 v0, 26, v0
	v_add_u32_e32 v0, v1, v0
	v_ashrrev_i32_e32 v11, 6, v0
	v_ashrrev_i32_e32 v0, 31, v14
	v_lshrrev_b32_e32 v0, 26, v0
	v_add_u32_e32 v0, v14, v0
	v_ashrrev_i32_e32 v12, 6, v0
	v_lshlrev_b32_e32 v0, 3, v12
	v_and_b32_e32 v0, -16, v0
	v_add_u32_e32 v0, v11, v0
	v_and_b32_e32 v3, 3, v11
	v_and_or_b32 v3, v0, s4, v3
	s_lshr_b32 s4, s3, 29
	s_add_i32 s4, s2, s4
	s_ashr_i32 s5, s24, 6
	s_ashr_i32 s7, s4, 3
	s_and_b32 s4, s4, -8
	s_ashr_i32 s6, s24, 8
	s_lshl_b32 s25, s5, 10
	s_sub_i32 s4, s2, s4
	s_cmp_lt_i32 s4, 0
	s_movk_i32 s26, 0xc7
	s_cselect_b32 s10, s26, 0xc0
	s_mul_i32 s4, s4, s10
	v_lshrrev_b32_e32 v4, 2, v0
	v_lshlrev_b32_e32 v5, 1, v0
	s_add_i32 s4, s4, s7
	v_and_b32_e32 v4, 4, v4
	v_and_b32_e32 v5, 24, v5
	s_mul_hi_i32 s7, s4, 0x2e8ba2e9
	v_or3_b32 v3, v3, v4, v5
	v_mul_i32_i24_e32 v5, 64, v11
	s_lshr_b32 s10, s7, 31
	s_ashr_i32 s7, s7, 6
	v_sub_u32_e32 v1, v1, v5
	s_add_i32 s7, s7, s10
	v_lshlrev_b32_e32 v4, 5, v12
	v_ashrrev_i16_sdwa v1, v2, sext(v1) dst_sel:DWORD dst_unused:UNUSED_PAD src0_sel:DWORD src1_sel:BYTE_0
	s_lshl_b32 s12, s7, 3
	v_and_b32_e32 v4, 32, v4
	v_bfe_i32 v13, v1, 0, 16
	s_sub_i32 s10, 36, s12
	s_mulk_i32 s7, 0x160
	v_add_lshl_u32 v1, v4, v13, 1
	s_min_u32 s13, s10, 8
	s_sub_i32 s7, s4, s7
	v_lshl_add_u32 v132, v3, 12, v1
	s_sext_i32_i16 s4, s7
	v_cvt_f32_ubyte0_e32 v3, s13
	v_cvt_f32_i32_e32 v2, s4
	v_rcp_iflag_f32_e32 v4, v3
	v_lshl_add_u32 v134, v0, 12, v1
	s_ashr_i32 s4, s4, 30
	s_or_b32 s4, s4, 1
	v_mul_f32_e32 v0, v2, v4
	v_trunc_f32_e32 v0, v0
	v_fma_f32 v1, -v0, v3, v2
	v_cvt_i32_f32_e32 v0, v0
	v_cmp_ge_f32_e64 s[10:11], |v1|, v3
	s_and_b64 s[10:11], s[10:11], exec
	s_cselect_b32 s4, s4, 0
	v_readfirstlane_b32 s10, v0
	s_add_i32 s4, s10, s4
	s_mul_i32 s10, s4, s13
	s_sub_i32 s7, s7, s10
	s_sext_i32_i16 s7, s7
	s_add_i32 s16, s12, s7
	s_cmp_eq_u32 s97, 0
	s_cbranch_scc1 .Lt5_sel
	s_sub_i32 s7, s2, 0xd0
	s_and_b32 s16, s7, 3
	s_add_i32 s16, s16, 32
	s_lshr_b32 s4, s7, 2
	s_add_i32 s4, s4, 32
.Lt5_sel:
	s_ashr_i32 s17, s16, 31
	s_bfe_i64 s[12:13], s[4:5], 0x100000
	s_lshl_b64 s[10:11], s[16:17], 20
	s_lshl_b64 s[12:13], s[12:13], 20
	v_readlane_b32 s14, v239, 7
	v_readlane_b32 s15, v239, 8
	s_add_u32 s20, s14, s12
	s_addc_u32 s21, s15, s13
	s_add_i32 s17, s25, 0
	s_add_i32 m0, s17, 0x10000
	v_mov_b32_e32 v133, 0
	global_load_lds_dwordx4 v132, s[20:21]
	s_add_i32 m0, s17, 0x12000
	s_add_u32 s18, s0, s10
	global_load_lds_dwordx4 v128, s[20:21]
	s_addc_u32 s19, s1, s11
	s_mov_b32 m0, s17
	s_add_i32 s27, s17, 0x2000
	global_load_lds_dwordx4 v134, s[18:19]
	s_mov_b32 m0, s27
	s_add_u32 s10, s20, 0x80000
	global_load_lds_dwordx4 v130, s[18:19]
	s_addc_u32 s11, s21, 0
	s_add_i32 m0, s17, 0x14000
	v_mov_b32_e32 v129, v133
	global_load_lds_dwordx4 v132, s[10:11]
	s_add_i32 m0, s17, 0x16000
	v_mov_b32_e32 v135, v133
	global_load_lds_dwordx4 v128, s[10:11]
	s_add_u32 s10, s18, 0x80000
	s_addc_u32 s11, s19, 0
	s_add_i32 s33, s17, 0x4000
	s_mov_b32 m0, s33
	s_add_i32 s35, s17, 0x6000
	global_load_lds_dwordx4 v134, s[10:11]
	s_mov_b32 m0, s35
	v_mov_b32_e32 v131, v133
	global_load_lds_dwordx4 v130, s[10:11]
	s_lshl_b32 s36, s97, 8
	v_lshl_add_u64 v[6:7], s[20:21], 0, v[132:133]
	v_lshl_add_u64 v[4:5], s[20:21], 0, v[128:129]
	v_lshl_add_u64 v[2:3], s[18:19], 0, v[134:135]
	s_cmp_lg_u32 s6, 1
	v_lshl_add_u64 v[0:1], s[18:19], 0, v[130:131]
	s_cbranch_scc1 .LBB0_939
	s_barrier

.LBB0_948:
	s_waitcnt vmcnt(0)
	s_barrier
	s_cmp_lg_u32 s97, 0
	s_cbranch_scc1 .Lt5_after
	s_mov_b64 s[0:1], exec
	v_readlane_b32 s4, v239, 4
	v_readlane_b32 s5, v239, 5
	s_and_b64 s[4:5], s[0:1], s[4:5]
	s_mov_b64 exec, s[4:5]
	s_cbranch_execz .LBB0_996
	s_add_i32 s4, 0, 0x21ff0
	v_mov_b32_e32 v0, s4
	s_waitcnt vmcnt(0) expcnt(0) lgkmcnt(0)
	ds_read_b32 v2, v0
	s_add_i32 s4, 0, 0x21ff4
	v_mov_b32_e32 v0, s4
	ds_read_b32 v0, v0
	s_waitcnt lgkmcnt(1)
	v_cmp_ne_u32_e32 vcc, 0, v2
	s_cbranch_vccnz .LBB0_964
	s_mov_b32 s10, 1
	v_mov_b32_e32 v16, 0
	s_branch .LBB0_952

.LBB0_996:
	s_or_b64 exec, exec, s[0:1]
	s_cmp_lt_u32 s2, 0xd0
	s_cbranch_scc1 .Lt5_p6
	s_mov_b32 s97, 1
	s_add_u32 s0, s30, 0xa600000
	s_addc_u32 s1, s31, 0
	s_add_u32 s8, s30, 0x17d29000
	s_addc_u32 s9, s31, 0
	s_branch .Lt5_entry
.Lt5_after:
	s_mov_b32 s97, 2
.Lt5_p6:
	v_readlane_b32 s0, v239, 2
	s_waitcnt lgkmcnt(0)
	v_mov_b32_e32 v0, v176
	s_barrier
	s_lshl_b32 s22, s0, 9
	s_mov_b32 s0, 0x18c00
	v_add_u32_e32 v144, s96, v0
	s_cmp_eq_u32 s97, 2
	s_cbranch_scc1 .Lt5_own
	s_mov_b32 s4, 0x2e8ba2e9
	v_mul_hi_i32 v1, v144, s4
	v_lshrrev_b32_e32 v2, 31, v1
	v_ashrrev_i32_e32 v1, 7, v1
	v_add_u32_e32 v1, v1, v2
	v_mul_i32_i24_e32 v2, 0x2c0, v1
	v_sub_u32_e32 v2, v144, v2
	s_movk_i32 s6, 0x13f
	v_cmp_lt_u32_e32 vcc, 0x7f, v1
	v_cmp_lt_u32_e64 s[4:5], s6, v2
	v_mov_b32_e32 v1, 0x7fffffff
	s_nop 1
	s_and_b64 vcc, vcc, s[4:5]
	s_nop 1
	v_cndmask_b32_e32 v144, v144, v1, vcc
	s_branch .Lt5_tasks
.Lt5_own:
	s_sub_i32 s4, s2, 0xd0
	s_and_b32 s5, s4, 3
	s_lshl_b32 s5, s5, 2
	s_add_i32 s5, s5, 0x80
	s_lshr_b32 s4, s4, 2
	s_lshl_b32 s4, s4, 5
	s_add_i32 s4, s4, 0x140
	s_mul_i32 s5, s5, 0x2c0
	s_add_i32 s4, s4, s5
	v_lshrrev_b32_e32 v1, 7, v0
	v_mul_u32_u24_e32 v1, 0x2c0, v1
	v_and_b32_e32 v2, 31, v0
	v_add3_u32 v144, v1, v2, s4

.LBB0_999:
	s_mov_b32 s4, 0x2e8ba2e9
	v_mul_hi_i32 v0, v145, s4
	v_lshrrev_b32_e32 v1, 31, v0
	v_ashrrev_i32_e32 v0, 7, v0
	v_add_u32_e32 v67, v0, v1
	v_mul_i32_i24_e32 v0, 0x2c0, v67
	v_sub_u32_e32 v0, v145, v0
	v_lshlrev_b32_e32 v64, 3, v0
	v_ashrrev_i32_e32 v65, 31, v64
	v_lshlrev_b64 v[56:57], 2, v[64:65]
	v_lshl_add_u64 v[4:5], s[56:57], 0, v[56:57]
	v_lshl_add_u64 v[12:13], s[10:11], 0, v[56:57]
	v_lshl_add_u64 v[20:21], s[12:13], 0, v[56:57]
	v_lshl_add_u64 v[28:29], s[14:15], 0, v[56:57]
	v_lshl_add_u64 v[36:37], s[16:17], 0, v[56:57]
	v_lshl_add_u64 v[44:45], s[18:19], 0, v[56:57]
	v_lshl_add_u64 v[52:53], s[58:59], 0, v[56:57]
	v_lshl_add_u64 v[60:61], s[8:9], 0, v[56:57]
	global_load_dwordx4 v[0:3], v[4:5], off offset:16
	s_nop 0
	global_load_dwordx4 v[4:7], v[4:5], off
	s_nop 0
	global_load_dwordx4 v[8:11], v[12:13], off offset:16
	s_nop 0
	global_load_dwordx4 v[12:15], v[12:13], off
	s_nop 0
	global_load_dwordx4 v[16:19], v[20:21], off offset:16
	s_nop 0
	global_load_dwordx4 v[20:23], v[20:21], off
	s_nop 0
	global_load_dwordx4 v[24:27], v[28:29], off offset:16
	s_nop 0
	global_load_dwordx4 v[28:31], v[28:29], off
	s_nop 0
	global_load_dwordx4 v[32:35], v[36:37], off offset:16
	s_nop 0
	global_load_dwordx4 v[36:39], v[36:37], off
	s_nop 0
	global_load_dwordx4 v[40:43], v[44:45], off offset:16
	s_nop 0
	global_load_dwordx4 v[44:47], v[44:45], off
	s_nop 0
	global_load_dwordx4 v[48:51], v[52:53], off offset:16
	s_nop 0
	global_load_dwordx4 v[52:55], v[52:53], off
	s_nop 0
	global_load_dwordx4 v[56:59], v[60:61], off offset:16
	s_nop 0
	global_load_dwordx4 v[60:63], v[60:61], off
	v_lshlrev_b32_e32 v66, 6, v67
	s_cmp_lg_u32 s97, 2
	s_cbranch_scc1 .Lt5_r0
	v_bfe_u32 v146, v176, 5, 2
	v_lshl_add_u32 v66, v146, 4, v66
.Lt5_r0:
	v_and_b32_e32 v67, 31, v67
	s_mov_b32 s4, 0x15fff
	v_cmp_gt_i32_e32 vcc, s23, v145
	v_cmp_ne_u32_e64 s[6:7], 0, v67
	v_cmp_lt_i32_e64 s[4:5], s4, v145
	v_mov_b32_e32 v120, 0
	s_and_b64 s[34:35], vcc, s[6:7]
	v_mov_b32_e32 v121, 0
	v_mov_b32_e32 v122, 0
	v_mov_b32_e32 v123, 0
	v_mov_b32_e32 v128, 0
	v_mov_b32_e32 v129, 0
	v_mov_b32_e32 v130, 0
	v_mov_b32_e32 v131, 0
	v_mov_b32_e32 v132, 0
	v_mov_b32_e32 v133, 0
	v_mov_b32_e32 v134, 0
	v_mov_b32_e32 v135, 0
	v_mov_b32_e32 v124, 0
	v_mov_b32_e32 v125, 0
	v_mov_b32_e32 v126, 0
	v_mov_b32_e32 v127, 0
	s_and_saveexec_b64 s[6:7], s[34:35]
	s_cbranch_execz .LBB0_1001
	v_add_u32_e32 v67, -2, v66
	v_lshl_add_u64 v[68:69], v[64:65], 1, s[30:31]
	v_mad_i64_i32 v[70:71], s[34:35], v67, s24, v[68:69]
	v_add_co_u32_e32 v72, vcc, 0x2000, v70
	v_add_u32_e32 v67, -1, v66
	s_nop 0
	v_addc_co_u32_e32 v73, vcc, 0, v71, vcc
	v_mad_i64_i32 v[68:69], s[34:35], v67, s24, v[68:69]
	global_load_dwordx4 v[120:123], v[70:71], off
	global_load_dwordx4 v[124:127], v[72:73], off offset:3072
	v_add_co_u32_e32 v70, vcc, 0x2000, v68
	s_nop 1
	v_addc_co_u32_e32 v71, vcc, 0, v69, vcc
	global_load_dwordx4 v[128:131], v[68:69], off
	global_load_dwordx4 v[132:135], v[70:71], off offset:3072
.LBB0_1001:
	s_or_b64 exec, exec, s[6:7]
	v_lshl_add_u64 v[146:147], v[64:65], 2, s[78:79]
	v_lshlrev_b64 v[148:149], 1, v[64:65]
	v_mov_b64_e32 v[64:65], s[30:31]
	s_movk_i32 s6, 0x2c00
	v_add_u32_e32 v177, 0xffffe000, v66
	v_mad_i64_i32 v[150:151], s[6:7], v66, s6, v[64:65]
	v_mad_i64_i32 v[152:153], s[6:7], v66, s24, v[64:65]
	s_mov_b32 s33, 0
	s_cmp_eq_u32 s97, 2
	s_cselect_b32 s33, 48, 0
	v_subrev_u32_e32 v177, s33, v177
	s_branch .LBB0_1003

.LBB0_1005:
	s_or_b64 exec, exec, s[0:1]
	v_add_u32_e32 v144, s96, v176
	s_cmp_lg_u32 s97, 2
	s_cbranch_scc1 .Lt5_nocopy
	s_mov_b64 s[18:19], exec
	s_sub_i32 s4, s2, 0xd0
	s_and_b32 s5, s4, 3
	s_lshl_b32 s5, s5, 6
	s_lshr_b32 s4, s4, 2
	s_add_i32 s4, s4, 32
	s_lshl_b32 s4, s4, 5
	v_lshrrev_b32_e32 v16, 5, v176
	v_add_u32_e32 v16, s5, v16
	v_mul_u32_u24_e32 v16, 0x580, v16
	v_and_b32_e32 v17, 31, v176
	v_add3_u32 v16, v16, v17, s4
	s_add_i32 s5, s5, 64
	s_mul_i32 s5, s5, 0x580
	s_movk_i32 s16, 0x5800
	s_mov_b32 s4, 0xba2e8ba3
	v_mov_b32_e32 v0, v16
